# prep step 4: waves of roles 1-3 run a copy without counted vmcnt waits (no stall on their own image stores' acknowledgement)
# speedup vs baseline: 1.0116x; 1.0028x over previous
; #define PG8_LAS __attribute__((address_space(3)))
; __device__ __forceinline__ unsigned pk2c(float a, float b) { const f32x2_ v = {a, b}; const bf16x2_ r = __builtin_convertvector(v, bf16x2_); return __builtin_bit_cast(unsigned, r); }
; #define MFMA16(a, b, c) __builtin_amdgcn_mfma_f32_16x16x32_bf16((a), (b), (c), 0, 0, 0)
; __device__ __forceinline__ void phase_prep(const Args& a, PG8_LAS unsigned char* lds) {
;     ...
;         {
;             bf16x8 tf[4][2];
; #pragma unroll
;             for (int it = 0; it < 4; ++it)
; #pragma unroll
;                 for (int s = 0; s < 2; ++s) tf[it][s] = *(const PG8_LAS bf16x8*)(Tu + ((16 * it + r) * 72 + 32 * s + 8 * q) * 2);
; #pragma unroll
;             for (int cc = 0; cc < 2; ++cc) { const int ct = 2 * lw + cc;
;                 const bf16x8 v0 = pv[cc][0], v1 = pv[cc][1];
; #pragma unroll
;                 for (int it = 0; it < 4; ++it) { f32x4 acc = {0.f, 0.f, 0.f, 0.f}; acc = MFMA16(tf[it][0], v0, acc); acc = MFMA16(tf[it][1], v1, acc);
;                     u32x2 w; w.x = pk2c(acc[0], acc[1]); w.y = pk2c(acc[2], acc[3]);
;                     *(u32x2*)(uT + (16 * ct + r) * 64 + 16 * it + 4 * q) = w; } }
; #pragma unroll
;             for (int it = 0; it < 4; ++it)
; #pragma unroll
;                 for (int s = 0; s < 2; ++s) tf[it][s] = *(const PG8_LAS bf16x8*)(Tw + ((16 * it + r) * 72 + 32 * s + 8 * q) * 2);
; #pragma unroll
;             for (int cc = 0; cc < 2; ++cc) { const int dt = 2 * lw + cc;
;                 const bf16x8 k0 = pk[cc][0], k1 = pk[cc][1];
;                 const int o4 = 16 * dt + 4 * q, dpos = (o4 & ~31) + perm32s(o4 & 31);
; #pragma unroll
;                 for (int it = 0; it < 4; ++it) { f32x4 acc = {0.f, 0.f, 0.f, 0.f}; acc = MFMA16(k0, tf[it][0], acc); acc = MFMA16(k1, tf[it][1], acc);
;                     u32x2 w; w.x = pk2c(acc[0], acc[1]); w.y = pk2c(acc[2], acc[3]);
;                     *(u32x2*)(wp + (16 * it + r) * 128 + dpos) = w; } }
;         }
.LBB0_252:
	s_waitcnt lgkmcnt(0)
	s_barrier
	v_readlane_b32 s40, v253, 53
	v_readlane_b32 s41, v253, 54
	s_andn2_b64 vcc, exec, s[40:41]
	s_cbranch_vccnz .Lst4_r0
	ds_read_b128 v[32:35], v228 offset:17408
	ds_read_b128 v[36:39], v228 offset:17472
	ds_read_b128 v[44:47], v228 offset:19712
	ds_read_b128 v[48:51], v228 offset:19776
	ds_read_b128 v[56:59], v228 offset:22016
	ds_read_b128 v[60:63], v228 offset:22080
	s_waitcnt lgkmcnt(5)
	v_mfma_f32_16x16x32_bf16 v[40:43], v[32:35], v[0:3], 0
	ds_read_b128 v[68:71], v228 offset:24320
	ds_read_b128 v[72:75], v228 offset:24384
	v_mov_b32_e32 v113, v97
	v_mfma_f32_16x16x32_bf16 v[32:35], v[32:35], v[20:23], 0
	v_mov_b32_e32 v115, v97
	s_mov_b64 s[20:21], 0xc000
	v_mov_b32_e32 v117, v97
	s_waitcnt lgkmcnt(6)
	v_mfma_f32_16x16x32_bf16 v[40:43], v[36:39], v[4:7], v[40:43]
	v_mov_b32_e32 v121, v97
	v_mov_b32_e32 v123, v97
	v_mov_b32_e32 v119, v97
	s_waitcnt lgkmcnt(5)
	v_mfma_f32_16x16x32_bf16 v[52:55], v[44:47], v[0:3], 0
	v_mov_b32_e32 v125, v97
	s_add_i32 s38, s38, 1
	s_add_i32 s31, s31, s34
	v_mfma_f32_16x16x32_bf16 v[32:35], v[36:39], v[28:31], v[32:35]
	v_lshl_add_u64 v[36:37], s[18:19], 0, v[112:113]
	v_lshl_add_u64 v[80:81], v[36:37], 0, v[114:115]
	v_lshl_add_u64 v[82:83], v[80:81], 0, s[20:21]
	s_waitcnt lgkmcnt(3)
	v_mfma_f32_16x16x32_bf16 v[64:67], v[56:59], v[0:3], 0
	s_cmp_lt_i32 s38, s98
	v_mfma_f32_16x16x32_bf16 v[36:39], v[44:47], v[20:23], 0
	v_cvt_pk_bf16_f32 v44, v40, v41
	v_cvt_pk_bf16_f32 v45, v42, v43
	v_add_co_u32_e32 v46, vcc, s35, v80
	v_mfma_f32_16x16x32_bf16 v[40:43], v[56:59], v[20:23], 0
	s_nop 0
	v_addc_co_u32_e32 v47, vcc, 0, v81, vcc
	global_store_dwordx2 v[46:47], v[44:45], off
	v_mfma_f32_16x16x32_bf16 v[52:55], v[48:51], v[4:7], v[52:55]
	v_lshl_add_u64 v[80:81], s[18:19], 0, v[116:117]
	s_waitcnt lgkmcnt(2)
	v_mfma_f32_16x16x32_bf16 v[64:67], v[60:63], v[4:7], v[64:67]
	v_mfma_f32_16x16x32_bf16 v[40:43], v[60:63], v[28:31], v[40:43]
	v_cvt_pk_bf16_f32 v60, v32, v33
	v_cvt_pk_bf16_f32 v61, v34, v35
	ds_read_b128 v[32:35], v228 offset:28928
	v_mfma_f32_16x16x32_bf16 v[36:39], v[48:51], v[28:31], v[36:39]
	v_cvt_pk_bf16_f32 v44, v52, v53
	v_cvt_pk_bf16_f32 v45, v54, v55
	global_store_dwordx2 v[82:83], v[44:45], off offset:32
	s_waitcnt lgkmcnt(2)
	v_mfma_f32_16x16x32_bf16 v[76:79], v[68:71], v[0:3], 0
	global_store_dwordx2 v[82:83], v[60:61], off offset:2048
	ds_read_b128 v[60:63], v228 offset:28992
	v_cvt_pk_bf16_f32 v48, v64, v65
	v_mfma_f32_16x16x32_bf16 v[44:47], v[68:71], v[20:23], 0
	v_cvt_pk_bf16_f32 v49, v66, v67
	v_cvt_pk_bf16_f32 v36, v36, v37
	v_cvt_pk_bf16_f32 v37, v38, v39
	s_waitcnt lgkmcnt(1)
	v_mfma_f32_16x16x32_bf16 v[64:67], v[8:11], v[32:35], 0
	global_store_dwordx2 v[82:83], v[36:37], off offset:2080
	ds_read_b128 v[36:39], v228 offset:31232
	global_store_dwordx2 v[82:83], v[48:49], off offset:64
	v_mfma_f32_16x16x32_bf16 v[32:35], v[16:19], v[32:35], 0
	ds_read_b128 v[48:51], v228 offset:26624
	v_mfma_f32_16x16x32_bf16 v[76:79], v[72:75], v[4:7], v[76:79]
	v_mfma_f32_16x16x32_bf16 v[44:47], v[72:75], v[28:31], v[44:47]
	v_cvt_pk_bf16_f32 v72, v40, v41
	v_cvt_pk_bf16_f32 v73, v42, v43
	global_store_dwordx2 v[82:83], v[72:73], off offset:2112
	ds_read_b128 v[72:75], v228 offset:33536
	s_waitcnt lgkmcnt(3)
	v_mfma_f32_16x16x32_bf16 v[64:67], v[12:15], v[60:63], v[64:67]
	s_nop 0
	v_cvt_pk_bf16_f32 v52, v76, v77
	v_cvt_pk_bf16_f32 v53, v78, v79
	ds_read_b128 v[40:43], v228 offset:31296
	v_mfma_f32_16x16x32_bf16 v[32:35], v[24:27], v[60:63], v[32:35]
	v_cvt_pk_bf16_f32 v44, v44, v45
	v_cvt_pk_bf16_f32 v45, v46, v47
	global_store_dwordx2 v[82:83], v[52:53], off offset:96
	ds_read_b128 v[52:55], v228 offset:26688
	s_waitcnt lgkmcnt(4)
	v_mfma_f32_16x16x32_bf16 v[68:71], v[8:11], v[36:39], 0
	global_store_dwordx2 v[82:83], v[44:45], off offset:2144
	ds_read_b128 v[44:47], v228 offset:33600
	v_cvt_pk_bf16_f32 v64, v64, v65
	v_mfma_f32_16x16x32_bf16 v[36:39], v[16:19], v[36:39], 0
	v_cvt_pk_bf16_f32 v65, v66, v67
	v_cvt_pk_bf16_f32 v66, v32, v33
	v_cvt_pk_bf16_f32 v67, v34, v35
	s_waitcnt lgkmcnt(4)
	v_mfma_f32_16x16x32_bf16 v[56:59], v[8:11], v[48:51], 0
	v_lshl_add_u64 v[82:83], v[80:81], 0, v[118:119]
	v_lshl_add_u64 v[60:61], v[80:81], 0, v[124:125]
	s_waitcnt lgkmcnt(3)
	v_mfma_f32_16x16x32_bf16 v[76:79], v[8:11], v[72:75], 0
	v_mfma_f32_16x16x32_bf16 v[48:51], v[16:19], v[48:51], 0
	v_mfma_f32_16x16x32_bf16 v[32:35], v[16:19], v[72:75], 0
	s_waitcnt lgkmcnt(2)
	v_mfma_f32_16x16x32_bf16 v[68:71], v[12:15], v[40:43], v[68:71]
	v_mfma_f32_16x16x32_bf16 v[36:39], v[24:27], v[40:43], v[36:39]
	s_waitcnt lgkmcnt(1)
	v_mfma_f32_16x16x32_bf16 v[56:59], v[12:15], v[52:55], v[56:59]
	s_waitcnt lgkmcnt(0)
	v_mfma_f32_16x16x32_bf16 v[76:79], v[12:15], v[44:47], v[76:79]
	v_mfma_f32_16x16x32_bf16 v[48:51], v[24:27], v[52:55], v[48:51]
	v_lshl_add_u64 v[54:55], v[80:81], 0, v[120:121]
	s_nop 0
	v_cvt_pk_bf16_f32 v52, v68, v69
	v_cvt_pk_bf16_f32 v53, v70, v71
	v_mfma_f32_16x16x32_bf16 v[32:35], v[24:27], v[44:47], v[32:35]
	v_lshl_add_u64 v[70:71], v[80:81], 0, v[122:123]
	global_store_dwordx4 v[54:55], v[64:67], off
	v_cvt_pk_bf16_f32 v54, v36, v37
	v_cvt_pk_bf16_f32 v55, v38, v39
	v_cvt_pk_bf16_f32 v56, v56, v57
	v_cvt_pk_bf16_f32 v57, v58, v59
	v_cvt_pk_bf16_f32 v68, v76, v77
	v_cvt_pk_bf16_f32 v69, v78, v79
	v_cvt_pk_bf16_f32 v58, v48, v49
	v_cvt_pk_bf16_f32 v59, v50, v51
	global_store_dwordx4 v[70:71], v[52:55], off
	v_cvt_pk_bf16_f32 v70, v32, v33
	v_cvt_pk_bf16_f32 v71, v34, v35
	global_store_dwordx4 v[82:83], v[56:59], off
	global_store_dwordx4 v[60:61], v[68:71], off
	s_branch .Lst4_end
; #define PG8_LAS __attribute__((address_space(3)))
; __device__ __forceinline__ unsigned pk2c(float a, float b) { const f32x2_ v = {a, b}; const bf16x2_ r = __builtin_convertvector(v, bf16x2_); return __builtin_bit_cast(unsigned, r); }
; #define MFMA16(a, b, c) __builtin_amdgcn_mfma_f32_16x16x32_bf16((a), (b), (c), 0, 0, 0)
; __device__ __forceinline__ void phase_prep(const Args& a, PG8_LAS unsigned char* lds) {
;     ...
;         {
;             bf16x8 tf[4][2];
; #pragma unroll
;             for (int it = 0; it < 4; ++it)
; #pragma unroll
;                 for (int s = 0; s < 2; ++s) tf[it][s] = *(const PG8_LAS bf16x8*)(Tu + ((16 * it + r) * 72 + 32 * s + 8 * q) * 2);
; #pragma unroll
;             for (int cc = 0; cc < 2; ++cc) { const int ct = 2 * lw + cc;
;                 const bf16x8 v0 = pv[cc][0], v1 = pv[cc][1];
; #pragma unroll
;                 for (int it = 0; it < 4; ++it) { f32x4 acc = {0.f, 0.f, 0.f, 0.f}; acc = MFMA16(tf[it][0], v0, acc); acc = MFMA16(tf[it][1], v1, acc);
;                     u32x2 w; w.x = pk2c(acc[0], acc[1]); w.y = pk2c(acc[2], acc[3]);
;                     *(u32x2*)(uT + (16 * ct + r) * 64 + 16 * it + 4 * q) = w; } }
; #pragma unroll
;             for (int it = 0; it < 4; ++it)
; #pragma unroll
;                 for (int s = 0; s < 2; ++s) tf[it][s] = *(const PG8_LAS bf16x8*)(Tw + ((16 * it + r) * 72 + 32 * s + 8 * q) * 2);
; #pragma unroll
;             for (int cc = 0; cc < 2; ++cc) { const int dt = 2 * lw + cc;
;                 const bf16x8 k0 = pk[cc][0], k1 = pk[cc][1];
;                 const int o4 = 16 * dt + 4 * q, dpos = (o4 & ~31) + perm32s(o4 & 31);
; #pragma unroll
;                 for (int it = 0; it < 4; ++it) { f32x4 acc = {0.f, 0.f, 0.f, 0.f}; acc = MFMA16(k0, tf[it][0], acc); acc = MFMA16(k1, tf[it][1], acc);
;                     u32x2 w; w.x = pk2c(acc[0], acc[1]); w.y = pk2c(acc[2], acc[3]);
;                     *(u32x2*)(wp + (16 * it + r) * 128 + dpos) = w; } }
;         }
;         __syncthreads();
.Lst4_r0:
	ds_read_b128 v[32:35], v228 offset:17408
	ds_read_b128 v[36:39], v228 offset:17472
	ds_read_b128 v[44:47], v228 offset:19712
	ds_read_b128 v[48:51], v228 offset:19776
	ds_read_b128 v[56:59], v228 offset:22016
	ds_read_b128 v[60:63], v228 offset:22080
	s_waitcnt vmcnt(7) lgkmcnt(5)
	v_mfma_f32_16x16x32_bf16 v[40:43], v[32:35], v[0:3], 0
	ds_read_b128 v[68:71], v228 offset:24320
	ds_read_b128 v[72:75], v228 offset:24384
	v_mov_b32_e32 v113, v97
	s_waitcnt vmcnt(3)
	v_mfma_f32_16x16x32_bf16 v[32:35], v[32:35], v[20:23], 0
	v_mov_b32_e32 v115, v97
	s_mov_b64 s[20:21], 0xc000
	v_mov_b32_e32 v117, v97
	s_waitcnt lgkmcnt(6)
	v_mfma_f32_16x16x32_bf16 v[40:43], v[36:39], v[4:7], v[40:43]
	v_mov_b32_e32 v121, v97
	v_mov_b32_e32 v123, v97
	v_mov_b32_e32 v119, v97
	s_waitcnt lgkmcnt(5)
	v_mfma_f32_16x16x32_bf16 v[52:55], v[44:47], v[0:3], 0
	v_mov_b32_e32 v125, v97
	s_add_i32 s38, s38, 1
	s_add_i32 s31, s31, s34
	s_waitcnt vmcnt(2)
	v_mfma_f32_16x16x32_bf16 v[32:35], v[36:39], v[28:31], v[32:35]
	v_lshl_add_u64 v[36:37], s[18:19], 0, v[112:113]
	v_lshl_add_u64 v[80:81], v[36:37], 0, v[114:115]
	v_lshl_add_u64 v[82:83], v[80:81], 0, s[20:21]
	s_waitcnt lgkmcnt(3)
	v_mfma_f32_16x16x32_bf16 v[64:67], v[56:59], v[0:3], 0
	s_cmp_lt_i32 s38, s98
	v_mfma_f32_16x16x32_bf16 v[36:39], v[44:47], v[20:23], 0
	v_cvt_pk_bf16_f32 v44, v40, v41
	v_cvt_pk_bf16_f32 v45, v42, v43
	v_add_co_u32_e32 v46, vcc, s35, v80
	v_mfma_f32_16x16x32_bf16 v[40:43], v[56:59], v[20:23], 0
	s_nop 0
	v_addc_co_u32_e32 v47, vcc, 0, v81, vcc
	global_store_dwordx2 v[46:47], v[44:45], off
	v_mfma_f32_16x16x32_bf16 v[52:55], v[48:51], v[4:7], v[52:55]
	v_lshl_add_u64 v[80:81], s[18:19], 0, v[116:117]
	s_waitcnt lgkmcnt(2)
	v_mfma_f32_16x16x32_bf16 v[64:67], v[60:63], v[4:7], v[64:67]
	v_mfma_f32_16x16x32_bf16 v[40:43], v[60:63], v[28:31], v[40:43]
	v_cvt_pk_bf16_f32 v60, v32, v33
	v_cvt_pk_bf16_f32 v61, v34, v35
	ds_read_b128 v[32:35], v228 offset:28928
	v_mfma_f32_16x16x32_bf16 v[36:39], v[48:51], v[28:31], v[36:39]
	v_cvt_pk_bf16_f32 v44, v52, v53
	v_cvt_pk_bf16_f32 v45, v54, v55
	global_store_dwordx2 v[82:83], v[44:45], off offset:32
	s_waitcnt lgkmcnt(2)
	v_mfma_f32_16x16x32_bf16 v[76:79], v[68:71], v[0:3], 0
	global_store_dwordx2 v[82:83], v[60:61], off offset:2048
	ds_read_b128 v[60:63], v228 offset:28992
	v_cvt_pk_bf16_f32 v48, v64, v65
	v_mfma_f32_16x16x32_bf16 v[44:47], v[68:71], v[20:23], 0
	v_cvt_pk_bf16_f32 v49, v66, v67
	v_cvt_pk_bf16_f32 v36, v36, v37
	v_cvt_pk_bf16_f32 v37, v38, v39
	s_waitcnt lgkmcnt(1)
	v_mfma_f32_16x16x32_bf16 v[64:67], v[8:11], v[32:35], 0
	global_store_dwordx2 v[82:83], v[36:37], off offset:2080
	ds_read_b128 v[36:39], v228 offset:31232
	global_store_dwordx2 v[82:83], v[48:49], off offset:64
	s_waitcnt vmcnt(6)
	v_mfma_f32_16x16x32_bf16 v[32:35], v[16:19], v[32:35], 0
	ds_read_b128 v[48:51], v228 offset:26624
	v_mfma_f32_16x16x32_bf16 v[76:79], v[72:75], v[4:7], v[76:79]
	v_mfma_f32_16x16x32_bf16 v[44:47], v[72:75], v[28:31], v[44:47]
	v_cvt_pk_bf16_f32 v72, v40, v41
	v_cvt_pk_bf16_f32 v73, v42, v43
	global_store_dwordx2 v[82:83], v[72:73], off offset:2112
	ds_read_b128 v[72:75], v228 offset:33536
	s_waitcnt lgkmcnt(3)
	v_mfma_f32_16x16x32_bf16 v[64:67], v[12:15], v[60:63], v[64:67]
	s_nop 0
	v_cvt_pk_bf16_f32 v52, v76, v77
	v_cvt_pk_bf16_f32 v53, v78, v79
	ds_read_b128 v[40:43], v228 offset:31296
	s_waitcnt vmcnt(6)
	v_mfma_f32_16x16x32_bf16 v[32:35], v[24:27], v[60:63], v[32:35]
	v_cvt_pk_bf16_f32 v44, v44, v45
	v_cvt_pk_bf16_f32 v45, v46, v47
	global_store_dwordx2 v[82:83], v[52:53], off offset:96
	ds_read_b128 v[52:55], v228 offset:26688
	s_waitcnt lgkmcnt(4)
	v_mfma_f32_16x16x32_bf16 v[68:71], v[8:11], v[36:39], 0
	global_store_dwordx2 v[82:83], v[44:45], off offset:2144
	ds_read_b128 v[44:47], v228 offset:33600
	v_cvt_pk_bf16_f32 v64, v64, v65
	v_mfma_f32_16x16x32_bf16 v[36:39], v[16:19], v[36:39], 0
	v_cvt_pk_bf16_f32 v65, v66, v67
	v_cvt_pk_bf16_f32 v66, v32, v33
	v_cvt_pk_bf16_f32 v67, v34, v35
	s_waitcnt lgkmcnt(4)
	v_mfma_f32_16x16x32_bf16 v[56:59], v[8:11], v[48:51], 0
	v_lshl_add_u64 v[82:83], v[80:81], 0, v[118:119]
	v_lshl_add_u64 v[60:61], v[80:81], 0, v[124:125]
	s_waitcnt lgkmcnt(3)
	v_mfma_f32_16x16x32_bf16 v[76:79], v[8:11], v[72:75], 0
	v_mfma_f32_16x16x32_bf16 v[48:51], v[16:19], v[48:51], 0
	v_mfma_f32_16x16x32_bf16 v[32:35], v[16:19], v[72:75], 0
	s_waitcnt lgkmcnt(2)
	v_mfma_f32_16x16x32_bf16 v[68:71], v[12:15], v[40:43], v[68:71]
	v_mfma_f32_16x16x32_bf16 v[36:39], v[24:27], v[40:43], v[36:39]
	s_waitcnt lgkmcnt(1)
	v_mfma_f32_16x16x32_bf16 v[56:59], v[12:15], v[52:55], v[56:59]
	s_waitcnt lgkmcnt(0)
	v_mfma_f32_16x16x32_bf16 v[76:79], v[12:15], v[44:47], v[76:79]
	v_mfma_f32_16x16x32_bf16 v[48:51], v[24:27], v[52:55], v[48:51]
	v_lshl_add_u64 v[54:55], v[80:81], 0, v[120:121]
	s_nop 0
	v_cvt_pk_bf16_f32 v52, v68, v69
	v_cvt_pk_bf16_f32 v53, v70, v71
	v_mfma_f32_16x16x32_bf16 v[32:35], v[24:27], v[44:47], v[32:35]
	v_lshl_add_u64 v[70:71], v[80:81], 0, v[122:123]
	global_store_dwordx4 v[54:55], v[64:67], off
	v_cvt_pk_bf16_f32 v54, v36, v37
	v_cvt_pk_bf16_f32 v55, v38, v39
	v_cvt_pk_bf16_f32 v56, v56, v57
	v_cvt_pk_bf16_f32 v57, v58, v59
	v_cvt_pk_bf16_f32 v68, v76, v77
	v_cvt_pk_bf16_f32 v69, v78, v79
	v_cvt_pk_bf16_f32 v58, v48, v49
	v_cvt_pk_bf16_f32 v59, v50, v51
	global_store_dwordx4 v[70:71], v[52:55], off
	v_cvt_pk_bf16_f32 v70, v32, v33
	v_cvt_pk_bf16_f32 v71, v34, v35
	global_store_dwordx4 v[82:83], v[56:59], off
	global_store_dwordx4 v[60:61], v[68:71], off
.Lst4_end:
	s_barrier
	s_cbranch_scc0 .LBB0_300
